# WO epilogue: residual loads batched 2x16 (was 16 serialized round trips)
# baseline (speedup 1.0000x reference)
; __device__ __forceinline__ u32x2 pk4(f32x4 v) { u32x2 r; r.x = pk2(v.x, v.y); r.y = pk2(v.z, v.w); return r; }
; __device__ __forceinline__ f32x4 unpk4(u32x2 w) { f32x4 r; r.x = bflo(w.x); r.y = bfhi(w.x); r.z = bflo(w.y); r.w = bfhi(w.y); return r; }
; template <int EPI>
; __device__ __forceinline__ void epilogue(const Params& p, f32x4 (&acc)[2][2][4][2], const int pm, const int pn, const int wr, const int wc, const int fr, const int fq) {
;     ...
;   } else if constexpr (EPI == EPI_WO || EPI == EPI_DOWN) {
;     const bf16_t* X1b = (const bf16_t*)(ws + OFF_X1B);
; #pragma unroll
;     for (int ai = 0; ai < 2; ++ai)
; #pragma unroll
;       for (int m = 0; m < 4; ++m) {
;         const int row = pm * 256 + ai * 128 + wr * 64 + m * 16 + fr;
; #pragma unroll
;         for (int bj = 0; bj < 2; ++bj) {
;           const int col = pn * 256 + bj * 128 + wc * 32 + fq * 8;
;           f32x4 x0, x1;
;           if constexpr (EPI == EPI_WO) { const float* xp = p.in[0] + (size_t)row * DM + col; x0 = *(const f32x4*)xp; x1 = *(const f32x4*)(xp + 4); }
;           else { const u32x4 xw = *(const u32x4*)(X1b + (size_t)row * DM + col); x0 = unpk4(u32x2{xw.x, xw.y}); x1 = unpk4(u32x2{xw.z, xw.w}); }
;           f32x4 v0 = acc[ai][bj][m][0], v1 = acc[ai][bj][m][1];
;           v0.x += ALPHA_F * x0.x; v0.y += ALPHA_F * x0.y; v0.z += ALPHA_F * x0.z; v0.w += ALPHA_F * x0.w;
;           v1.x += ALPHA_F * x1.x; v1.y += ALPHA_F * x1.y; v1.z += ALPHA_F * x1.z; v1.w += ALPHA_F * x1.w;
;           const u32x2 lo = pk4(v0), hi = pk4(v1);
;           *(u32x4*)((bf16_t*)(ws + (EPI == EPI_WO ? OFF_PRE1 : OFF_PRE2)) + (size_t)row * DM + col) = u32x4{lo.x, lo.y, hi.x, hi.y};
;         }
;       }
.LBB0_831:
	v_lshl_add_u32 v142, s4, 8, v148
	v_lshl_or_b32 v144, s6, 8, v151
	v_readlane_b32 s68, v244, 14
	v_readlane_b32 s69, v244, 15
	v_readlane_b32 s70, v244, 16
	v_readlane_b32 s71, v244, 17
	v_readlane_b32 s72, v244, 18
	v_readlane_b32 s73, v244, 19
	v_readlane_b32 s74, v244, 20
	v_readlane_b32 s75, v244, 21
	v_readlane_b32 s76, v244, 22
	v_readlane_b32 s77, v244, 23
	v_readlane_b32 s78, v244, 24
	v_readlane_b32 s79, v244, 25
	v_readlane_b32 s80, v244, 26
	v_readlane_b32 s81, v244, 27
	v_readlane_b32 s82, v244, 28
	v_readlane_b32 s83, v244, 29
	s_mov_b64 s[52:53], s[68:69]
	s_mov_b64 s[54:55], s[70:71]
	v_lshlrev_b32_e32 v146, 12, v142
	v_lshl_add_u32 v146, v144, 2, v146
	v_lshlrev_b32_e32 v147, 11, v142
	v_lshl_add_u32 v147, v144, 1, v147
	s_add_u32 s98, s68, 0x0
	s_addc_u32 s99, s69, 0
	s_add_u32 s100, s96, 0x0
	s_addc_u32 s101, s97, 0
	global_load_dwordx4 v[156:159], v146, s[98:99] offset:0
	global_load_dwordx4 v[160:163], v146, s[98:99] offset:16
	global_load_dwordx4 v[164:167], v146, s[98:99] offset:512
	global_load_dwordx4 v[168:171], v146, s[98:99] offset:528
	s_add_u32 s98, s98, 0x10000
	s_addc_u32 s99, s99, 0
	global_load_dwordx4 v[172:175], v146, s[98:99] offset:0
	global_load_dwordx4 v[176:179], v146, s[98:99] offset:16
	global_load_dwordx4 v[188:191], v146, s[98:99] offset:512
	global_load_dwordx4 v[192:195], v146, s[98:99] offset:528
	s_add_u32 s98, s98, 0x10000
	s_addc_u32 s99, s99, 0
	global_load_dwordx4 v[196:199], v146, s[98:99] offset:0
	global_load_dwordx4 v[200:203], v146, s[98:99] offset:16
	global_load_dwordx4 v[204:207], v146, s[98:99] offset:512
	global_load_dwordx4 v[208:211], v146, s[98:99] offset:528
	s_add_u32 s98, s98, 0x10000
	s_addc_u32 s99, s99, 0
	global_load_dwordx4 v[212:215], v146, s[98:99] offset:0
	global_load_dwordx4 v[216:219], v146, s[98:99] offset:16
	global_load_dwordx4 v[220:223], v146, s[98:99] offset:512
	global_load_dwordx4 v[142:145], v146, s[98:99] offset:528
	s_waitcnt vmcnt(14)
	v_pk_fma_f32 v[156:157], v[156:157], s[14:15], v[126:127] op_sel_hi:[1,0,1]
	v_pk_fma_f32 v[158:159], v[158:159], s[14:15], v[128:129] op_sel_hi:[1,0,1]
	v_pk_fma_f32 v[160:161], v[160:161], s[14:15], v[122:123] op_sel_hi:[1,0,1]
	v_pk_fma_f32 v[162:163], v[162:163], s[14:15], v[124:125] op_sel_hi:[1,0,1]
	v_cvt_pk_bf16_f32 v156, v156, v157
	v_cvt_pk_bf16_f32 v157, v158, v159
	v_cvt_pk_bf16_f32 v158, v160, v161
	v_cvt_pk_bf16_f32 v159, v162, v163
	global_store_dwordx4 v147, v[156:159], s[100:101] offset:0
	s_waitcnt vmcnt(13)
	v_pk_fma_f32 v[164:165], v[164:165], s[14:15], v[110:111] op_sel_hi:[1,0,1]
	v_pk_fma_f32 v[166:167], v[166:167], s[14:15], v[112:113] op_sel_hi:[1,0,1]
	v_pk_fma_f32 v[168:169], v[168:169], s[14:15], v[102:103] op_sel_hi:[1,0,1]
	v_pk_fma_f32 v[170:171], v[170:171], s[14:15], v[104:105] op_sel_hi:[1,0,1]
	v_cvt_pk_bf16_f32 v164, v164, v165
	v_cvt_pk_bf16_f32 v165, v166, v167
	v_cvt_pk_bf16_f32 v166, v168, v169
	v_cvt_pk_bf16_f32 v167, v170, v171
	global_store_dwordx4 v147, v[164:167], s[100:101] offset:256
	s_add_u32 s100, s100, 0x8000
	s_addc_u32 s101, s101, 0
	s_waitcnt vmcnt(12)
	v_pk_fma_f32 v[172:173], v[172:173], s[14:15], v[118:119] op_sel_hi:[1,0,1]
	v_pk_fma_f32 v[174:175], v[174:175], s[14:15], v[120:121] op_sel_hi:[1,0,1]
	v_pk_fma_f32 v[176:177], v[176:177], s[14:15], v[114:115] op_sel_hi:[1,0,1]
	v_pk_fma_f32 v[178:179], v[178:179], s[14:15], v[116:117] op_sel_hi:[1,0,1]
	v_cvt_pk_bf16_f32 v172, v172, v173
	v_cvt_pk_bf16_f32 v173, v174, v175
	v_cvt_pk_bf16_f32 v174, v176, v177
	v_cvt_pk_bf16_f32 v175, v178, v179
	global_store_dwordx4 v147, v[172:175], s[100:101] offset:0
	s_waitcnt vmcnt(11)
	v_pk_fma_f32 v[188:189], v[188:189], s[14:15], v[94:95] op_sel_hi:[1,0,1]
	v_pk_fma_f32 v[190:191], v[190:191], s[14:15], v[96:97] op_sel_hi:[1,0,1]
	v_pk_fma_f32 v[192:193], v[192:193], s[14:15], v[86:87] op_sel_hi:[1,0,1]
	v_pk_fma_f32 v[194:195], v[194:195], s[14:15], v[88:89] op_sel_hi:[1,0,1]
	v_cvt_pk_bf16_f32 v188, v188, v189
	v_cvt_pk_bf16_f32 v189, v190, v191
	v_cvt_pk_bf16_f32 v190, v192, v193
	v_cvt_pk_bf16_f32 v191, v194, v195
	global_store_dwordx4 v147, v[188:191], s[100:101] offset:256
	s_add_u32 s100, s100, 0x8000
	s_addc_u32 s101, s101, 0
	s_waitcnt vmcnt(10)
	v_pk_fma_f32 v[196:197], v[196:197], s[14:15], v[106:107] op_sel_hi:[1,0,1]
	v_pk_fma_f32 v[198:199], v[198:199], s[14:15], v[108:109] op_sel_hi:[1,0,1]
	v_pk_fma_f32 v[200:201], v[200:201], s[14:15], v[98:99] op_sel_hi:[1,0,1]
	v_pk_fma_f32 v[202:203], v[202:203], s[14:15], v[100:101] op_sel_hi:[1,0,1]
	v_cvt_pk_bf16_f32 v196, v196, v197
	v_cvt_pk_bf16_f32 v197, v198, v199
	v_cvt_pk_bf16_f32 v198, v200, v201
	v_cvt_pk_bf16_f32 v199, v202, v203
	global_store_dwordx4 v147, v[196:199], s[100:101] offset:0
	s_waitcnt vmcnt(9)
	v_pk_fma_f32 v[204:205], v[204:205], s[14:15], v[78:79] op_sel_hi:[1,0,1]
	v_pk_fma_f32 v[206:207], v[206:207], s[14:15], v[80:81] op_sel_hi:[1,0,1]
	v_pk_fma_f32 v[208:209], v[208:209], s[14:15], v[74:75] op_sel_hi:[1,0,1]
	v_pk_fma_f32 v[210:211], v[210:211], s[14:15], v[76:77] op_sel_hi:[1,0,1]
	v_cvt_pk_bf16_f32 v204, v204, v205
	v_cvt_pk_bf16_f32 v205, v206, v207
	v_cvt_pk_bf16_f32 v206, v208, v209
	v_cvt_pk_bf16_f32 v207, v210, v211
	global_store_dwordx4 v147, v[204:207], s[100:101] offset:256
	s_add_u32 s100, s100, 0x8000
	s_addc_u32 s101, s101, 0
	s_waitcnt vmcnt(8)
	v_pk_fma_f32 v[212:213], v[212:213], s[14:15], v[90:91] op_sel_hi:[1,0,1]
	v_pk_fma_f32 v[214:215], v[214:215], s[14:15], v[92:93] op_sel_hi:[1,0,1]
	v_pk_fma_f32 v[216:217], v[216:217], s[14:15], v[82:83] op_sel_hi:[1,0,1]
	v_pk_fma_f32 v[218:219], v[218:219], s[14:15], v[84:85] op_sel_hi:[1,0,1]
	v_cvt_pk_bf16_f32 v212, v212, v213
	v_cvt_pk_bf16_f32 v213, v214, v215
	v_cvt_pk_bf16_f32 v214, v216, v217
	v_cvt_pk_bf16_f32 v215, v218, v219
	global_store_dwordx4 v147, v[212:215], s[100:101] offset:0
	s_waitcnt vmcnt(7)
; __device__ __forceinline__ u32x2 pk4(f32x4 v) { u32x2 r; r.x = pk2(v.x, v.y); r.y = pk2(v.z, v.w); return r; }
; __device__ __forceinline__ f32x4 unpk4(u32x2 w) { f32x4 r; r.x = bflo(w.x); r.y = bfhi(w.x); r.z = bflo(w.y); r.w = bfhi(w.y); return r; }
; template <int EPI>
; __device__ __forceinline__ void epilogue(const Params& p, f32x4 (&acc)[2][2][4][2], const int pm, const int pn, const int wr, const int wc, const int fr, const int fq) {
;     ...
;     for (int ai = 0; ai < 2; ++ai)
; #pragma unroll
;       for (int m = 0; m < 4; ++m) {
;         const int row = pm * 256 + ai * 128 + wr * 64 + m * 16 + fr;
; #pragma unroll
;         for (int bj = 0; bj < 2; ++bj) {
;           const int col = pn * 256 + bj * 128 + wc * 32 + fq * 8;
;           f32x4 x0, x1;
;           if constexpr (EPI == EPI_WO) { const float* xp = p.in[0] + (size_t)row * DM + col; x0 = *(const f32x4*)xp; x1 = *(const f32x4*)(xp + 4); }
;           else { const u32x4 xw = *(const u32x4*)(X1b + (size_t)row * DM + col); x0 = unpk4(u32x2{xw.x, xw.y}); x1 = unpk4(u32x2{xw.z, xw.w}); }
;           f32x4 v0 = acc[ai][bj][m][0], v1 = acc[ai][bj][m][1];
;           v0.x += ALPHA_F * x0.x; v0.y += ALPHA_F * x0.y; v0.z += ALPHA_F * x0.z; v0.w += ALPHA_F * x0.w;
;           v1.x += ALPHA_F * x1.x; v1.y += ALPHA_F * x1.y; v1.z += ALPHA_F * x1.z; v1.w += ALPHA_F * x1.w;
;           const u32x2 lo = pk4(v0), hi = pk4(v1);
;           *(u32x4*)((bf16_t*)(ws + (EPI == EPI_WO ? OFF_PRE1 : OFF_PRE2)) + (size_t)row * DM + col) = u32x4{lo.x, lo.y, hi.x, hi.y};
;         }
	v_pk_fma_f32 v[220:221], v[220:221], s[14:15], v[70:71] op_sel_hi:[1,0,1]
	v_pk_fma_f32 v[222:223], v[222:223], s[14:15], v[72:73] op_sel_hi:[1,0,1]
	v_pk_fma_f32 v[142:143], v[142:143], s[14:15], v[66:67] op_sel_hi:[1,0,1]
	v_pk_fma_f32 v[144:145], v[144:145], s[14:15], v[68:69] op_sel_hi:[1,0,1]
	v_cvt_pk_bf16_f32 v220, v220, v221
	v_cvt_pk_bf16_f32 v221, v222, v223
	v_cvt_pk_bf16_f32 v222, v142, v143
	v_cvt_pk_bf16_f32 v223, v144, v145
	global_store_dwordx4 v147, v[220:223], s[100:101] offset:256
	s_add_u32 s98, s68, 0x80000
	s_addc_u32 s99, s69, 0
	s_add_u32 s100, s96, 0x40000
	s_addc_u32 s101, s97, 0
	global_load_dwordx4 v[156:159], v146, s[98:99] offset:0
	global_load_dwordx4 v[160:163], v146, s[98:99] offset:16
	global_load_dwordx4 v[164:167], v146, s[98:99] offset:512
	global_load_dwordx4 v[168:171], v146, s[98:99] offset:528
	s_add_u32 s98, s98, 0x10000
	s_addc_u32 s99, s99, 0
	global_load_dwordx4 v[172:175], v146, s[98:99] offset:0
	global_load_dwordx4 v[176:179], v146, s[98:99] offset:16
	global_load_dwordx4 v[188:191], v146, s[98:99] offset:512
	global_load_dwordx4 v[192:195], v146, s[98:99] offset:528
	s_add_u32 s98, s98, 0x10000
	s_addc_u32 s99, s99, 0
	global_load_dwordx4 v[196:199], v146, s[98:99] offset:0
	global_load_dwordx4 v[200:203], v146, s[98:99] offset:16
	global_load_dwordx4 v[204:207], v146, s[98:99] offset:512
	global_load_dwordx4 v[208:211], v146, s[98:99] offset:528
	s_add_u32 s98, s98, 0x10000
	s_addc_u32 s99, s99, 0
	global_load_dwordx4 v[212:215], v146, s[98:99] offset:0
	global_load_dwordx4 v[216:219], v146, s[98:99] offset:16
	global_load_dwordx4 v[220:223], v146, s[98:99] offset:512
	global_load_dwordx4 v[142:145], v146, s[98:99] offset:528
	s_waitcnt vmcnt(14)
	v_pk_fma_f32 v[156:157], v[156:157], s[14:15], v[62:63] op_sel_hi:[1,0,1]
	v_pk_fma_f32 v[158:159], v[158:159], s[14:15], v[64:65] op_sel_hi:[1,0,1]
	v_pk_fma_f32 v[160:161], v[160:161], s[14:15], v[58:59] op_sel_hi:[1,0,1]
	v_pk_fma_f32 v[162:163], v[162:163], s[14:15], v[60:61] op_sel_hi:[1,0,1]
	v_cvt_pk_bf16_f32 v156, v156, v157
	v_cvt_pk_bf16_f32 v157, v158, v159
	v_cvt_pk_bf16_f32 v158, v160, v161
	v_cvt_pk_bf16_f32 v159, v162, v163
	global_store_dwordx4 v147, v[156:159], s[100:101] offset:0
	s_waitcnt vmcnt(13)
	v_pk_fma_f32 v[164:165], v[164:165], s[14:15], v[46:47] op_sel_hi:[1,0,1]
	v_pk_fma_f32 v[166:167], v[166:167], s[14:15], v[48:49] op_sel_hi:[1,0,1]
	v_pk_fma_f32 v[168:169], v[168:169], s[14:15], v[38:39] op_sel_hi:[1,0,1]
	v_pk_fma_f32 v[170:171], v[170:171], s[14:15], v[40:41] op_sel_hi:[1,0,1]
	v_cvt_pk_bf16_f32 v164, v164, v165
	v_cvt_pk_bf16_f32 v165, v166, v167
	v_cvt_pk_bf16_f32 v166, v168, v169
	v_cvt_pk_bf16_f32 v167, v170, v171
	global_store_dwordx4 v147, v[164:167], s[100:101] offset:256
	s_add_u32 s100, s100, 0x8000
	s_addc_u32 s101, s101, 0
	s_waitcnt vmcnt(12)
	v_pk_fma_f32 v[172:173], v[172:173], s[14:15], v[54:55] op_sel_hi:[1,0,1]
	v_pk_fma_f32 v[174:175], v[174:175], s[14:15], v[56:57] op_sel_hi:[1,0,1]
	v_pk_fma_f32 v[176:177], v[176:177], s[14:15], v[50:51] op_sel_hi:[1,0,1]
	v_pk_fma_f32 v[178:179], v[178:179], s[14:15], v[52:53] op_sel_hi:[1,0,1]
	v_cvt_pk_bf16_f32 v172, v172, v173
	v_cvt_pk_bf16_f32 v173, v174, v175
	v_cvt_pk_bf16_f32 v174, v176, v177
	v_cvt_pk_bf16_f32 v175, v178, v179
	global_store_dwordx4 v147, v[172:175], s[100:101] offset:0
	s_waitcnt vmcnt(11)
	v_pk_fma_f32 v[188:189], v[188:189], s[14:15], v[30:31] op_sel_hi:[1,0,1]
	v_pk_fma_f32 v[190:191], v[190:191], s[14:15], v[32:33] op_sel_hi:[1,0,1]
	v_pk_fma_f32 v[192:193], v[192:193], s[14:15], v[22:23] op_sel_hi:[1,0,1]
	v_pk_fma_f32 v[194:195], v[194:195], s[14:15], v[24:25] op_sel_hi:[1,0,1]
	v_cvt_pk_bf16_f32 v188, v188, v189
	v_cvt_pk_bf16_f32 v189, v190, v191
	v_cvt_pk_bf16_f32 v190, v192, v193
	v_cvt_pk_bf16_f32 v191, v194, v195
	global_store_dwordx4 v147, v[188:191], s[100:101] offset:256
	s_add_u32 s100, s100, 0x8000
	s_addc_u32 s101, s101, 0
	s_waitcnt vmcnt(10)
	v_pk_fma_f32 v[196:197], v[196:197], s[14:15], v[42:43] op_sel_hi:[1,0,1]
	v_pk_fma_f32 v[198:199], v[198:199], s[14:15], v[44:45] op_sel_hi:[1,0,1]
	v_pk_fma_f32 v[200:201], v[200:201], s[14:15], v[34:35] op_sel_hi:[1,0,1]
	v_pk_fma_f32 v[202:203], v[202:203], s[14:15], v[36:37] op_sel_hi:[1,0,1]
	v_cvt_pk_bf16_f32 v196, v196, v197
	v_cvt_pk_bf16_f32 v197, v198, v199
	v_cvt_pk_bf16_f32 v198, v200, v201
	v_cvt_pk_bf16_f32 v199, v202, v203
	global_store_dwordx4 v147, v[196:199], s[100:101] offset:0
	s_waitcnt vmcnt(9)
	v_pk_fma_f32 v[204:205], v[204:205], s[14:15], v[14:15] op_sel_hi:[1,0,1]
	v_pk_fma_f32 v[206:207], v[206:207], s[14:15], v[16:17] op_sel_hi:[1,0,1]
	v_pk_fma_f32 v[208:209], v[208:209], s[14:15], v[10:11] op_sel_hi:[1,0,1]
	v_pk_fma_f32 v[210:211], v[210:211], s[14:15], v[12:13] op_sel_hi:[1,0,1]
	v_cvt_pk_bf16_f32 v204, v204, v205
	v_cvt_pk_bf16_f32 v205, v206, v207
	v_cvt_pk_bf16_f32 v206, v208, v209
	v_cvt_pk_bf16_f32 v207, v210, v211
	global_store_dwordx4 v147, v[204:207], s[100:101] offset:256
	s_add_u32 s100, s100, 0x8000
	s_addc_u32 s101, s101, 0
	s_waitcnt vmcnt(8)
	v_pk_fma_f32 v[212:213], v[212:213], s[14:15], v[26:27] op_sel_hi:[1,0,1]
	v_pk_fma_f32 v[214:215], v[214:215], s[14:15], v[28:29] op_sel_hi:[1,0,1]
	v_pk_fma_f32 v[216:217], v[216:217], s[14:15], v[18:19] op_sel_hi:[1,0,1]
	v_pk_fma_f32 v[218:219], v[218:219], s[14:15], v[20:21] op_sel_hi:[1,0,1]
	v_cvt_pk_bf16_f32 v212, v212, v213
	v_cvt_pk_bf16_f32 v213, v214, v215
	v_cvt_pk_bf16_f32 v214, v216, v217
	v_cvt_pk_bf16_f32 v215, v218, v219
	global_store_dwordx4 v147, v[212:215], s[100:101] offset:0
	s_waitcnt vmcnt(7)
	v_pk_fma_f32 v[220:221], v[220:221], s[14:15], v[6:7] op_sel_hi:[1,0,1]
	v_pk_fma_f32 v[222:223], v[222:223], s[14:15], v[8:9] op_sel_hi:[1,0,1]
	v_pk_fma_f32 v[142:143], v[142:143], s[14:15], v[2:3] op_sel_hi:[1,0,1]
	v_pk_fma_f32 v[144:145], v[144:145], s[14:15], v[4:5] op_sel_hi:[1,0,1]
	v_cvt_pk_bf16_f32 v220, v220, v221
	v_cvt_pk_bf16_f32 v221, v222, v223
	v_cvt_pk_bf16_f32 v222, v142, v143
	v_cvt_pk_bf16_f32 v223, v144, v145
	global_store_dwordx4 v147, v[220:223], s[100:101] offset:256
	s_cbranch_execz .LBB0_829

; __global__ void __launch_bounds__(512) fwd_megakernel(Params p) {
;   extern __shared__ __attribute__((aligned(16))) char lds[];
	.amdhsa_kernel _Z14fwd_megakernel6Params
		.amdhsa_group_segment_fixed_size 0
		.amdhsa_private_segment_fixed_size 0
		.amdhsa_kernarg_size 496
		.amdhsa_user_sgpr_count 2
		.amdhsa_user_sgpr_dispatch_ptr 0
		.amdhsa_user_sgpr_queue_ptr 0
		.amdhsa_user_sgpr_kernarg_segment_ptr 1
		.amdhsa_user_sgpr_dispatch_id 0
		.amdhsa_user_sgpr_kernarg_preload_length 0
		.amdhsa_user_sgpr_kernarg_preload_offset 0
		.amdhsa_user_sgpr_private_segment_size 0
		.amdhsa_uses_dynamic_stack 0
		.amdhsa_enable_private_segment 0
		.amdhsa_system_sgpr_workgroup_id_x 1
		.amdhsa_system_sgpr_workgroup_id_y 0
		.amdhsa_system_sgpr_workgroup_id_z 0
		.amdhsa_system_sgpr_workgroup_info 0
		.amdhsa_system_vgpr_workitem_id 0
		.amdhsa_next_free_vgpr 245
		.amdhsa_next_free_sgpr 102
		.amdhsa_accum_offset 248
		.amdhsa_reserve_vcc 1
		.amdhsa_float_round_mode_32 0
		.amdhsa_float_round_mode_16_64 0
		.amdhsa_float_denorm_mode_32 3
		.amdhsa_float_denorm_mode_16_64 3
		.amdhsa_dx10_clamp 1
		.amdhsa_ieee_mode 1
		.amdhsa_fp16_overflow 0
		.amdhsa_tg_split 0
		.amdhsa_exception_fp_ieee_invalid_op 0
		.amdhsa_exception_fp_denorm_src 0
		.amdhsa_exception_fp_ieee_div_zero 0
		.amdhsa_exception_fp_ieee_overflow 0
		.amdhsa_exception_fp_ieee_underflow 0
		.amdhsa_exception_fp_ieee_inexact 0
		.amdhsa_exception_int_div_zero 0
	.end_amdhsa_kernel

; __global__ void __launch_bounds__(512) fwd_megakernel(Params p) {
;   extern __shared__ __attribute__((aligned(16))) char lds[];
.Lfunc_end0:
	.size	_Z14fwd_megakernel6Params, .Lfunc_end0-_Z14fwd_megakernel6Params
	.set _Z14fwd_megakernel6Params.num_vgpr, 245
	.set _Z14fwd_megakernel6Params.num_agpr, 0
	.set _Z14fwd_megakernel6Params.numbered_sgpr, 102
	.set _Z14fwd_megakernel6Params.num_named_barrier, 0
	.set _Z14fwd_megakernel6Params.private_seg_size, 0
	.set _Z14fwd_megakernel6Params.uses_vcc, 1
	.set _Z14fwd_megakernel6Params.uses_flat_scratch, 0
	.set _Z14fwd_megakernel6Params.has_dyn_sized_stack, 0
	.set _Z14fwd_megakernel6Params.has_recursion, 0
	.set _Z14fwd_megakernel6Params.has_indirect_call, 0

amdhsa.kernels:
  - .agpr_count:     0
    .args:
      - .offset:         0
        .size:           240
        .value_kind:     by_value
      - .offset:         240
        .size:           4
        .value_kind:     hidden_block_count_x
      - .offset:         244
        .size:           4
        .value_kind:     hidden_block_count_y
      - .offset:         248
        .size:           4
        .value_kind:     hidden_block_count_z
      - .offset:         252
        .size:           2
        .value_kind:     hidden_group_size_x
      - .offset:         254
        .size:           2
        .value_kind:     hidden_group_size_y
      - .offset:         256
        .size:           2
        .value_kind:     hidden_group_size_z
      - .offset:         258
        .size:           2
        .value_kind:     hidden_remainder_x
      - .offset:         260
        .size:           2
        .value_kind:     hidden_remainder_y
      - .offset:         262
        .size:           2
        .value_kind:     hidden_remainder_z
      - .offset:         280
        .size:           8
        .value_kind:     hidden_global_offset_x
      - .offset:         288
        .size:           8
        .value_kind:     hidden_global_offset_y
      - .offset:         296
        .size:           8
        .value_kind:     hidden_global_offset_z
      - .offset:         304
        .size:           2
        .value_kind:     hidden_grid_dims
      - .offset:         360
        .size:           4
        .value_kind:     hidden_dynamic_lds_size
    .group_segment_fixed_size: 0
    .kernarg_segment_align: 8
    .kernarg_segment_size: 496
    .language:       OpenCL C
    .language_version:
      - 2
      - 0
    .max_flat_workgroup_size: 512
    .name:           _Z14fwd_megakernel6Params
    .private_segment_fixed_size: 0
    .sgpr_count:     108
    .sgpr_spill_count: 68
    .symbol:         _Z14fwd_megakernel6Params.kd
    .uniform_work_group_size: 1
    .uses_dynamic_stack: false
    .vgpr_count:     245
    .vgpr_spill_count: 0
    .wavefront_size: 64
